# P7 out-projection tile order re-blocked like P10 (4x8 per XCD-round, MIX rows stream once)
# baseline (speedup 1.0000x reference)
.LBB0_1354:
	v_ashrrev_i32_e32 v1, 31, v8
	v_lshrrev_b32_e32 v1, 26, v1
	v_add_u32_e32 v1, v8, v1
	v_ashrrev_i32_e32 v9, 6, v1
	v_bfe_i32 v1, v8, 27, 1
	v_lshlrev_b32_e32 v0, 4, v8
	v_lshrrev_b32_e32 v1, 22, v1
	v_add_u32_e32 v1, v0, v1
	v_and_b32_e32 v1, 0xfffffc00, v1
	v_sub_u32_e32 v1, v0, v1
	v_lshrrev_b32_e32 v2, 4, v1
	v_bitop3_b32 v1, v2, v1, 32 bitop3:0x6c
	v_ashrrev_i32_e32 v3, 31, v1
	v_lshrrev_b32_e32 v3, 26, v3
	v_add_u32_e32 v3, v1, v3
	v_lshlrev_b32_e32 v2, 3, v9
	v_ashrrev_i32_e32 v10, 6, v3
	v_and_b32_e32 v3, 0xc0, v3
	v_and_b32_e32 v2, -16, v2
	v_sub_u32_e32 v1, v1, v3
	v_mov_b32_e32 v3, 1
	s_ashr_i32 s8, s3, 3
	v_readlane_b32 s6, v254, 14
	v_add_u32_e32 v2, v10, v2
	v_ashrrev_i16_sdwa v1, v3, sext(v1) dst_sel:DWORD dst_unused:UNUSED_PAD src0_sel:DWORD src1_sel:BYTE_0
	s_add_u32 s3, s6, 0x3000000
	v_lshlrev_b32_e32 v4, 5, v9
	v_bfe_i32 v11, v1, 0, 16
	v_lshlrev_b32_e32 v1, 1, v2
	v_lshrrev_b32_e32 v5, 2, v2
	v_and_b32_e32 v6, 3, v10
	s_mov_b32 s6, 0xfffe0
	v_and_b32_e32 v4, 32, v4
	v_and_b32_e32 v1, 24, v1
	v_and_b32_e32 v5, 4, v5
	v_and_or_b32 v6, v2, s6, v6
	v_or3_b32 v1, v6, v5, v1
	v_add_lshl_u32 v4, v4, v11, 1
	v_add_u32_e32 v0, 0x2000, v0
	v_readlane_b32 s7, v254, 15
	v_lshl_add_u32 v130, v1, 12, v4
	v_ashrrev_i32_e32 v1, 31, v0
	s_addc_u32 s13, s7, 0
	v_lshrrev_b32_e32 v1, 22, v1
	s_add_i32 s8, s10, s8
	v_add_u32_e32 v1, v0, v1
	s_ashr_i32 s9, s8, 31
	v_ashrrev_i32_e32 v12, 10, v1
	s_lshr_b32 s9, s9, 26
	v_mul_i32_i24_e32 v1, 0x400, v12
	s_add_i32 s9, s8, s9
	v_sub_u32_e32 v0, v0, v1
	s_ashr_i32 s10, s9, 6
	s_andn2_b32 s9, s9, 63
	v_lshrrev_b32_e32 v1, 4, v0
	s_sub_i32 s8, s8, s9
	v_bitop3_b32 v0, v1, v0, 32 bitop3:0x6c
	s_bfe_i32 s9, s8, 0x80000
	v_lshl_add_u32 v128, v2, 12, v4
	v_ashrrev_i32_e32 v2, 31, v0
	s_bfe_u32 s9, s9, 0x3000c
	v_lshrrev_b32_e32 v2, 26, v2
	s_add_i32 s9, s8, s9
	v_add_u32_e32 v2, v0, v2
	s_bfe_i32 s11, s9, 0x80000
	s_and_b32 s9, s9, 0xf8
	v_lshlrev_b32_e32 v1, 3, v12
	v_ashrrev_i32_e32 v13, 6, v2
	v_and_b32_e32 v2, 0xc0, v2
	s_sub_i32 s8, s8, s9
	v_and_b32_e32 v1, -16, v1
	v_sub_u32_e32 v0, v0, v2
	s_lshl_b32 s10, s10, 3
	s_sext_i32_i16 s11, s11
	s_sext_i32_i8 s8, s8
	v_add_u32_e32 v1, v13, v1
	v_ashrrev_i16_sdwa v0, v3, sext(v0) dst_sel:DWORD dst_unused:UNUSED_PAD src0_sel:DWORD src1_sel:BYTE_0
	v_and_b32_e32 v3, 3, v13
	s_lshr_b32 s12, s11, 3
	s_add_i32 s24, s10, s8
	s_and_b32 s10, s8, 3
	s_lshr_b32 s11, s8, 2
	s_andn2_b32 s24, s24, 7
	s_add_i32 s24, s24, s10
	s_lshr_b32 s10, s12, 2
	s_lshl_b32 s10, s10, 2
	s_add_i32 s24, s24, s10
	s_and_b32 s12, s12, 3
	s_lshl_b32 s12, s12, 1
	s_add_i32 s12, s12, s11
	v_and_or_b32 v3, v1, s6, v3
	s_ashr_i32 s6, s0, 6
	s_ashr_i32 s25, s24, 31
	s_bfe_i64 s[10:11], s[12:13], 0x100000
	s_ashr_i32 s7, s0, 8
	s_lshl_b32 s36, s6, 10
	s_lshl_b64 s[8:9], s[24:25], 20
	s_lshl_b64 s[10:11], s[10:11], 20
	s_add_u32 s42, s3, s10
	v_lshlrev_b32_e32 v4, 5, v12
	v_bfe_i32 v14, v0, 0, 16
	v_lshlrev_b32_e32 v0, 1, v1
	v_lshrrev_b32_e32 v2, 2, v1
	s_addc_u32 s43, s13, s11
	s_add_i32 s25, s36, 0
	v_and_b32_e32 v4, 32, v4
	v_and_b32_e32 v0, 24, v0
	v_and_b32_e32 v2, 4, v2
	s_add_i32 m0, s25, 0x10000
	v_or3_b32 v0, v3, v2, v0
	v_add_lshl_u32 v2, v4, v14, 1
	global_load_lds_dwordx4 v130, s[42:43]
	s_add_i32 m0, s25, 0x12000
	v_lshl_add_u32 v134, v0, 12, v2
	s_add_u32 s10, s42, 0x80000
	global_load_lds_dwordx4 v134, s[42:43]
	s_addc_u32 s11, s43, 0
	s_add_i32 m0, s25, 0x14000
	v_lshl_add_u32 v132, v1, 12, v2
	global_load_lds_dwordx4 v130, s[10:11]
	s_add_i32 m0, s25, 0x16000
	s_add_u32 s30, s28, s8
	s_addc_u32 s31, s29, s9
	s_add_i32 s37, s25, 0x2000
	global_load_lds_dwordx4 v134, s[10:11]
	s_mov_b32 m0, s25
	s_add_u32 s8, s30, 0x80000
	global_load_lds_dwordx4 v128, s[30:31]
	s_mov_b32 m0, s37
	s_addc_u32 s9, s31, 0
	s_add_i32 s38, s25, 0x4000
	global_load_lds_dwordx4 v132, s[30:31]
	s_mov_b32 m0, s38
	s_add_i32 s39, s25, 0x6000
	global_load_lds_dwordx4 v128, s[8:9]
	s_mov_b32 m0, s39
	v_mov_b32_e32 v131, 0
	global_load_lds_dwordx4 v132, s[8:9]
	v_readlane_b32 s8, v254, 3
	v_readlane_b32 s9, v254, 4
	s_load_dwordx2 s[8:9], s[8:9], 0xc0
	v_mov_b32_e32 v135, v131
	v_mov_b32_e32 v129, v131
	v_mov_b32_e32 v133, v131
	s_mov_b32 s46, 0
	v_lshl_add_u64 v[6:7], s[42:43], 0, v[130:131]
	v_lshl_add_u64 v[4:5], s[42:43], 0, v[134:135]
	v_lshl_add_u64 v[2:3], s[30:31], 0, v[128:129]
	s_cmp_lg_u32 s7, 1
	v_lshl_add_u64 v[0:1], s[30:31], 0, v[132:133]
	s_cbranch_scc1 .LBB0_1356
	s_barrier

.LBB0_1362:
	s_ashr_i32 s7, s7, 3
	s_add_i32 s7, s15, s7
	s_ashr_i32 s14, s7, 31
	s_lshr_b32 s14, s14, 26
	s_add_i32 s14, s7, s14
	s_ashr_i32 s15, s14, 6
	s_lshl_b32 s15, s15, 3
	s_sub_i32 s16, 64, s15
	s_min_i32 s17, s16, 8
	s_abs_i32 s16, s17
	v_cvt_f32_u32_e32 v0, s16
	s_sub_i32 s19, 0, s16
	s_andn2_b32 s14, s14, 63
	s_sub_i32 s7, s7, s14
	v_rcp_iflag_f32_e32 v0, v0
	s_abs_i32 s14, s7
	s_xor_b32 s18, s7, s17
	s_ashr_i32 s18, s18, 31
	v_mul_f32_e32 v0, 0x4f7ffffe, v0
	v_cvt_u32_f32_e32 v0, v0
	s_nop 0
	v_readfirstlane_b32 s22, v0
	s_mul_i32 s19, s19, s22
	s_mul_hi_u32 s19, s22, s19
	s_add_i32 s22, s22, s19
	s_mul_hi_u32 s19, s14, s22
	s_mul_i32 s22, s19, s16
	s_sub_i32 s14, s14, s22
	s_add_i32 s23, s19, 1
	s_sub_i32 s22, s14, s16
	s_cmp_ge_u32 s14, s16
	s_cselect_b32 s19, s23, s19
	s_cselect_b32 s14, s22, s14
	s_add_i32 s22, s19, 1
	s_cmp_ge_u32 s14, s16
	s_cselect_b32 s14, s22, s19
	s_xor_b32 s14, s14, s18
	s_sub_i32 s16, s14, s18
	s_mul_i32 s14, s16, s17
	s_sub_i32 s7, s7, s14
	s_add_i32 s18, s15, s7
	s_and_b32 s7, s18, 7
	s_lshr_b32 s14, s16, 2
	s_and_b32 s15, s16, 3
	s_andn2_b32 s18, s18, 7
	s_lshl_b32 s14, s14, 2
	s_add_i32 s18, s18, s14
	s_and_b32 s14, s7, 3
	s_add_i32 s18, s18, s14
	s_lshr_b32 s7, s7, 2
	s_lshl_b32 s15, s15, 1
	s_add_i32 s16, s15, s7
